# up-gemm-epilogue-both-wave-groups-aligned-per-unit-stagger
# speedup vs baseline: 1.0253x; 1.0148x over previous
; #define PG8_STAGE(bufoff, gbase, hoff, imm) do { _Pragma("unroll") for (int _i = 0; _i < 2; ++_i) { \
;         asm volatile("s_mov_b32 m0, %0\n\ts_nop 0\n\tglobal_load_lds_dwordx4 %1, %2" \
;             :: "s"(lds0 + (unsigned)((bufoff) + _i * 8192)), "v"(voff0), "s"((const char*)(gbase) + (size_t)(hoff) + (size_t)(_i * 8192)) : "memory"); } } while (0)
; #define PG8_WAIT_V(n) asm volatile("s_waitcnt vmcnt(" #n ")" ::: "memory")
; #define PG8_BAR __builtin_amdgcn_s_barrier()
; template <class Epi>
; __device__ __forceinline__ void gemm_phase(LAS unsigned char* lds, const Gemm g, const StaticOrder& S, const Epi& E) {
;     ...
;     const char* cA = (const char*)g.A + (size_t)cur.pm * tstepA + (size_t)(cur.pn >> g.gshift) * g.gstride; const char* cB = (const char*)g.Bt + (size_t)cur.pn * tstepB;
;     PG8_STAGE(PG8_SB(0, 0), cB, 0, 0); PG8_STAGE(PG8_SA(0, 0), cA, 0, 0); PG8_STAGE(PG8_SB(0, 1), cB, hB, 0); PG8_STAGE(PG8_SA(0, 1), cA, hA, 0);
;     if (wr == 1) PG8_BAR;
;     PG8_WAIT_V(4); PG8_BAR;
;     PG8_STAGE(PG8_SB(1, 0), cB + KS, 0, 0); PG8_STAGE(PG8_SA(1, 0), cA + KS, 0, 0); PG8_STAGE(PG8_SB(1, 1), cB + KS, hB, 0);
;     PG8_WAIT_V(6); PG8_BAR;
.LBB0_730:
	s_mov_b32 s2, 0
	v_mov_b32_e32 v0, v235
	v_readlane_b32 s4, v255, 10
	v_readlane_b32 s5, v255, 11
	v_readfirstlane_b32 s1, v0
	s_andn2_b64 vcc, exec, s[4:5]
	s_ashr_i32 s0, s1, 6
	s_cbranch_vccnz .LBB0_765
	s_ashr_i32 s3, s2, 31
	s_add_u32 s2, s96, s2
	s_addc_u32 s3, s97, s3
	s_load_dwordx4 s[4:7], s[2:3], 0x68
	s_load_dwordx2 s[8:9], s[2:3], 0x90
	v_readlane_b32 s2, v255, 43
	s_mul_i32 s2, s2, 0x2c00000
	v_lshlrev_b32_e32 v152, 4, v0
	s_waitcnt lgkmcnt(0)
	s_add_u32 s26, s8, 0xa630000
	s_addc_u32 s27, s9, 0
	s_add_u32 s2, s8, s2
	s_addc_u32 s3, s9, 0
	s_add_u32 s84, s2, 0x2200000
	s_addc_u32 s85, s3, 0
	s_lshl_b32 s11, s0, 10
	s_ashr_i32 s10, s1, 8
	s_add_i32 s89, s11, 0
	v_readlane_b32 s2, v255, 33
	v_readlane_b32 s3, v255, 34
	s_add_u32 s78, s84, s2
	s_addc_u32 s79, s85, s3
	s_add_i32 s28, s89, 0x10000
	s_add_i32 s29, s89, 0x12000
	s_add_u32 s2, s78, 0x2000
	s_mov_b32 m0, s28
	s_nop 0
	global_load_lds_dwordx4 v152, s[78:79]
	s_addc_u32 s3, s79, 0
	s_mov_b32 m0, s29
	s_nop 0
	global_load_lds_dwordx4 v152, s[2:3]
	v_readlane_b32 s2, v255, 31
	v_readlane_b32 s3, v255, 32
	s_add_u32 s76, s26, s2
	s_addc_u32 s77, s27, s3
	s_add_i32 s40, s89, 0x2000
	s_add_u32 s2, s76, 0x2000
	s_mov_b32 m0, s89
	s_nop 0
	global_load_lds_dwordx4 v152, s[76:77]
	s_addc_u32 s3, s77, 0
	s_add_i32 s41, s89, 0x14000
	s_mov_b32 m0, s40
	s_nop 0
	global_load_lds_dwordx4 v152, s[2:3]
	s_add_u32 s2, s78, 0x80000
	s_addc_u32 s3, s79, 0
	s_add_i32 s42, s89, 0x16000
	s_mov_b32 m0, s41
	s_nop 0
	global_load_lds_dwordx4 v152, s[2:3]
	s_add_u32 s2, s78, 0x82000
	s_addc_u32 s3, s79, 0
	s_add_i32 s43, s89, 0x4000
	s_mov_b32 m0, s42
	s_nop 0
	global_load_lds_dwordx4 v152, s[2:3]
	s_add_u32 s2, s76, 0x80000
	s_addc_u32 s3, s77, 0
	s_add_i32 s92, s89, 0x6000
	s_mov_b32 m0, s43
	s_nop 0
	global_load_lds_dwordx4 v152, s[2:3]
	s_add_u32 s2, s76, 0x82000
	s_addc_u32 s3, s77, 0
	s_mov_b32 m0, s92
	s_nop 0
	global_load_lds_dwordx4 v152, s[2:3]
	s_cmp_eq_u32 s10, 1
	s_cselect_b64 s[2:3], -1, 0
	s_cmp_lg_u32 s10, 1
	s_cbranch_scc1 .LBB0_733
.LBB0_733:
	s_add_u32 s30, s4, s88
	v_readlane_b32 s4, v255, 43
	s_addc_u32 s48, s5, 0
	s_mul_i32 s4, s4, 0xb000
	s_add_u32 s6, s6, s4
	s_addc_u32 s7, s7, 0
	s_add_u32 s52, s8, 0x12630000
	s_addc_u32 s53, s9, 0
	s_add_u32 s54, s8, 0x28630000
	s_addc_u32 s55, s9, 0
	s_add_u32 s56, s8, 0x29130000
	v_and_b32_e32 v1, 63, v0
	v_and_b32_e32 v153, 15, v0
	v_lshrrev_b32_e32 v2, 1, v0
	v_and_b32_e32 v154, 48, v0
	v_lshlrev_b32_e32 v0, 2, v0
	s_addc_u32 s57, s9, 0
	s_and_b32 s8, s0, 3
	s_lshl_b32 s4, s10, 13
	v_lshl_or_b32 v3, v153, 6, v154
	v_and_b32_e32 v0, 32, v0
	s_lshl_b32 s21, s10, 6
	s_waitcnt vmcnt(0)
	v_bitop3_b32 v4, v3, s4, v0 bitop3:0xde
	s_lshl_b32 s4, s8, 12
	s_add_i32 s16, s89, 0x18000
	v_bitop3_b32 v0, v3, s4, v0 bitop3:0xde
	s_add_u32 s4, s78, 0x4000
	s_addc_u32 s5, s79, 0
	s_add_i32 s17, s89, 0x1a000
	s_waitcnt vmcnt(4)
	s_barrier
	s_mov_b32 m0, s16
	s_nop 0
	global_load_lds_dwordx4 v152, s[4:5]
	s_add_u32 s4, s78, 0x6000
	s_addc_u32 s5, s79, 0
	s_add_i32 s24, s89, 0x8000
	s_mov_b32 m0, s17
	s_nop 0
	global_load_lds_dwordx4 v152, s[4:5]
	s_add_u32 s4, s76, 0x4000
	s_addc_u32 s5, s77, 0
	s_add_i32 s37, s89, 0xa000
	s_mov_b32 m0, s24
	s_nop 0
	global_load_lds_dwordx4 v152, s[4:5]
	s_add_u32 s4, s76, 0x6000
	s_addc_u32 s5, s77, 0
	s_add_i32 s97, s89, 0x1c000
	s_mov_b32 m0, s37
	s_nop 0
	global_load_lds_dwordx4 v152, s[4:5]
	s_add_u32 s4, s78, 0x84000
	s_addc_u32 s5, s79, 0
	s_add_i32 s38, s89, 0x1e000
	s_mov_b32 m0, s97
	s_nop 0
	global_load_lds_dwordx4 v152, s[4:5]
	s_add_u32 s4, s78, 0x86000
	s_addc_u32 s5, s79, 0
	s_cmp_lt_i32 s0, 4
	v_readlane_b32 s49, v255, 38
	s_mov_b32 m0, s38
	s_nop 0
	global_load_lds_dwordx4 v152, s[4:5]
	s_cselect_b64 s[58:59], -1, 0
	s_add_i32 s4, s49, s11
	s_add_i32 s39, s4, 0x2000
	s_add_i32 s34, s89, 0xc000
	s_add_u32 s4, s76, 0x84000
	s_addc_u32 s5, s77, 0
	s_mov_b32 m0, s34
	s_nop 0
	global_load_lds_dwordx4 v152, s[4:5]
	s_add_u32 s4, s76, 0x86000
	s_addc_u32 s5, s77, 0
	s_add_i32 s12, s89, 0xe000
	s_mov_b32 m0, s12
	s_nop 0
	global_load_lds_dwordx4 v152, s[4:5]
	s_lshl_b32 s9, s10, 11
	s_cmp_gt_i32 s10, 0
	s_cselect_b64 s[60:61], -1, 0
	s_cmp_gt_i32 s10, -2
	s_cselect_b64 s[64:65], -1, 0
	s_add_i32 s11, s49, s9
	s_cmpk_lt_u32 s1, 0x100
	s_cselect_b64 s[62:63], -1, 0
	s_bfe_u32 s12, s1, 0x10006
	s_lshl_b32 s1, s10, 3
	s_and_b32 s1, s1, 8
	v_cmp_gt_u32_e32 vcc, 2, v153
	s_or_b32 s1, s1, s12
	s_and_b64 s[66:67], s[62:63], vcc
	s_lshl_b32 s13, s1, 10
	s_add_i32 s25, s89, 0xe000
	s_mul_i32 s4, s0, 0xb000
	v_and_b32_e32 v2, 24, v2
	s_mul_hi_i32 s1, s0, 0xb000
	s_add_u32 s10, s30, s4
	s_addc_u32 s1, s48, s1
	v_lshl_or_b32 v155, s8, 5, v2
	v_lshlrev_b32_e32 v5, 10, v153
	s_cmp_eq_u32 s0, 3
	v_lshlrev_b32_e32 v2, 2, v155
	v_add_u32_e32 v6, s9, v5
	v_readlane_b32 s0, v255, 39
	v_readlane_b32 s8, v255, 40
	v_readlane_b32 s30, v255, 41
	v_readlane_b32 s48, v255, 42
	v_or_b32_e32 v5, 0xfffff800, v5
	s_waitcnt vmcnt(8)
	v_add_u32_e32 v3, s49, v2
	v_add_u32_e32 v157, s0, v2
	v_add_u32_e32 v158, s8, v2
	v_add_u32_e32 v159, s30, v2
	v_add_u32_e32 v160, s48, v2
	v_or_b32_e32 v8, 16, v2
	v_add_u32_e32 v9, s11, v5
	v_or_b32_e32 v10, 0x200, v2
	v_or_b32_e32 v2, 0x210, v2
	v_cmp_gt_u32_e32 vcc, 32, v1
	v_add_u32_e32 v6, 0xffffc800, v6
	v_add_u32_e32 v7, s9, v3
	v_add_u32_e32 v161, s0, v8
	v_add_u32_e32 v162, s8, v8
	v_add_u32_e32 v163, s30, v8
	v_add_u32_e32 v164, s48, v8
	v_add_u32_e32 v165, v9, v8
	v_add_u32_e32 v8, s11, v8
	v_add_u32_e32 v166, s0, v10
	v_add_u32_e32 v167, s8, v10
	v_add_u32_e32 v168, s30, v10
	v_add_u32_e32 v169, s48, v10
	v_add_u32_e32 v170, v9, v10
	v_add_u32_e32 v10, s11, v10
	v_add_u32_e32 v171, s0, v2
	v_add_u32_e32 v172, s8, v2
	v_add_u32_e32 v173, s30, v2
	v_add_u32_e32 v174, s48, v2
	v_add_u32_e32 v175, v9, v2
	v_add_u32_e32 v2, s11, v2
	v_cndmask_b32_e64 v1, v254, 0, vcc
	s_movk_i32 s0, 0x1f0
	s_cselect_b32 s30, s7, s1
	s_cselect_b32 s96, s6, s10
	v_readlane_b32 s6, v255, 29
	s_mov_b32 s86, s88
	s_mov_b32 s22, 0
	v_cmp_lt_u32_e64 s[4:5], 13, v153
	v_add_u32_e32 v156, -14, v153
	v_and_or_b32 v176, v152, s0, v1
	v_add_u32_e32 v177, 0x10000, v0
	v_add_u32_e32 v178, 0, v4
	v_add_u32_e32 v179, v3, v6
	v_add_u32_e32 v180, v8, v5
	v_add_u32_e32 v181, v10, v5
	v_add_u32_e32 v182, v2, v5
	v_add_u32_e32 v183, v7, v5
	v_readlane_b32 s1, v255, 22
	s_mov_b32 s88, s6
	s_barrier
	v_readlane_b32 s7, v255, 30
	s_branch .LBB0_735

; #define PG8_STAGE(bufoff, gbase, hoff, imm) do { _Pragma("unroll") for (int _i = 0; _i < 2; ++_i) { \
;         asm volatile("s_mov_b32 m0, %0\n\ts_nop 0\n\tglobal_load_lds_dwordx4 %1, %2" \
;             :: "s"(lds0 + (unsigned)((bufoff) + _i * 8192)), "v"(voff0), "s"((const char*)(gbase) + (size_t)(hoff) + (size_t)(_i * 8192)) : "memory"); } } while (0)
; #define PG8_LDA(dst, b, h) do { _Pragma("unroll") for (int m = 0; m < 4; ++m) _Pragma("unroll") for (int k = 0; k < 2; ++k) dst[m][k] = *(const LAS bf16x8*)(lds + PG8_SA(b, h) + aoff + m * 2048 + k * 1024); } while (0)
; #define PG8_LDB(dst, b, h) do { _Pragma("unroll") for (int n = 0; n < 2; ++n) _Pragma("unroll") for (int k = 0; k < 2; ++k) dst[n][k] = *(const LAS bf16x8*)(lds + PG8_SB(b, h) + boff + n * 2048 + k * 1024); } while (0)
; #define PG8_MMA(ai, bj, At, Bt) do { __builtin_amdgcn_s_setprio(1); _Pragma("unroll") for (int m = 0; m < 4; ++m) _Pragma("unroll") for (int n = 0; n < 2; ++n) _Pragma("unroll") for (int k = 0; k < 2; ++k) \
;         acc[ai][bj][m][n] = __builtin_amdgcn_mfma_f32_16x16x32_bf16(Bt[n][k], At[m][k], acc[ai][bj][m][n], 0, 0, 0); __builtin_amdgcn_s_setprio(0); } while (0)
; #define PG8_WAIT_L(n) asm volatile("s_waitcnt lgkmcnt(" #n ")" ::: "memory")
; template <class Epi>
; __device__ __forceinline__ void gemm_phase(LAS unsigned char* lds, const Gemm g, const StaticOrder& S, const Epi& E) {
;     ...
;     if (wr == 1) PG8_BAR;
;     ...
;         const bool has_next = S.next(ui + 1, nxt);
;         const char* nA = has_next ? (const char*)g.A + (size_t)nxt.pm * tstepA + (size_t)(nxt.pn >> g.gshift) * g.gstride : cA;
;         const char* nB = has_next ? (const char*)g.Bt + (size_t)nxt.pn * tstepB : cB;
;         for (int t = 0; t < nt; t += 2) {
;             const bool last = (t == nt - 2);
;             if (last) E.pre(cur, wid, lane, (unsigned)(size_t)(lds + STAGE_BYTES));
;             const char* aT = cA + (size_t)t * KS;
;             const char* a2 = last ? nA : aT + 2 * KS; const char* b2 = last ? nB : cB + (size_t)(t + 2) * KS;
;             PG8_LDB(B0, 0, 0); PG8_SCHED; PG8_LDA(At, 0, 0); PG8_STAGE(PG8_SA(1, 1), aT + KS, hA, 0);
;             PG8_WAIT_L(8); PG8_BAR; PG8_WAIT_L(0); PG8_MMA(0, 0, At, B0); PG8_BAR; PG8_SCHED;
;             PG8_LDB(B1, 0, 1); PG8_STAGE(PG8_SB(0, 0), b2, 0, 0);
;             PG8_BAR; PG8_WAIT_L(0); PG8_MMA(0, 1, At, B1); PG8_BAR;
.LBB0_737:
	s_ashr_i32 s71, s70, 31
	v_cmp_lt_i64_e32 vcc, s[8:9], v[198:199]
	s_lshl_b64 s[8:9], s[70:71], 20
	s_add_u32 s72, s26, s8
	s_addc_u32 s73, s27, s9
	s_and_b64 s[8:9], vcc, exec
	s_cselect_b32 s50, s73, s77
	s_cselect_b32 s51, s72, s76
	s_ashr_i32 s69, s68, 31
	s_lshl_b64 s[8:9], s[68:69], 20
	s_add_u32 s74, s84, s8
	s_addc_u32 s75, s85, s9
	s_and_b64 s[8:9], vcc, exec
	s_cselect_b32 s69, s75, s79
	s_cselect_b32 s0, s74, s78
	s_lshl_b32 s8, s1, 7
	s_ashr_i32 s9, s8, 31
	s_lshl_b64 s[10:11], s[8:9], 2
	s_add_u32 s10, s96, s10
	s_addc_u32 s11, s30, s11
	s_add_u32 s1, s78, 0x8000
	s_addc_u32 s9, s79, 0
	s_mov_b32 s71, -2
	ds_read_b128 v[128:131], v177
	ds_read_b128 v[132:135], v177 offset:1024
	ds_read_b128 v[136:139], v177 offset:2048
	ds_read_b128 v[140:143], v177 offset:3072
	v_readfirstlane_b32 s48, v235
	s_nop 1
	s_cmpk_lt_u32 s48, 0x100
	s_cbranch_scc1 .Lup_st_skip
	s_barrier
.Lup_st_skip:
	s_mov_b64 s[82:83], 0
	s_add_u32 s78, s76, 0x8000
	s_addc_u32 s79, s77, 0
	s_and_b64 s[48:49], s[82:83], exec
	s_cselect_b32 s81, s50, s79
	s_cselect_b32 s80, s51, s78
	ds_read_b128 v[144:147], v178
	ds_read_b128 v[148:151], v178 offset:1024
	ds_read_b128 v[184:187], v178 offset:2048
	ds_read_b128 v[200:203], v178 offset:3072
	ds_read_b128 v[204:207], v178 offset:4096
	ds_read_b128 v[208:211], v178 offset:5120
	ds_read_b128 v[212:215], v178 offset:6144
	ds_read_b128 v[236:239], v178 offset:7168
	s_waitcnt lgkmcnt(8)
	s_waitcnt vmcnt(10)
	s_barrier
	s_waitcnt lgkmcnt(7)
	v_mfma_f32_16x16x32_bf16 v[116:119], v[128:131], v[144:147], 0
	v_mfma_f32_16x16x32_bf16 v[80:83], v[136:139], v[144:147], 0
	s_waitcnt lgkmcnt(5)
	v_mfma_f32_16x16x32_bf16 v[88:91], v[128:131], v[184:187], 0
	v_mfma_f32_16x16x32_bf16 v[84:87], v[136:139], v[184:187], 0
	s_waitcnt lgkmcnt(3)
	v_mfma_f32_16x16x32_bf16 v[120:123], v[128:131], v[204:207], 0
	v_mfma_f32_16x16x32_bf16 v[92:95], v[136:139], v[204:207], 0
	s_waitcnt lgkmcnt(1)
	v_mfma_f32_16x16x32_bf16 v[124:127], v[128:131], v[212:215], 0
	v_mfma_f32_16x16x32_bf16 v[96:99], v[136:139], v[212:215], 0
	v_mfma_f32_16x16x32_bf16 v[116:119], v[132:135], v[148:151], v[116:119]
	v_mfma_f32_16x16x32_bf16 v[80:83], v[140:143], v[148:151], v[80:83]
	v_mfma_f32_16x16x32_bf16 v[88:91], v[132:135], v[200:203], v[88:91]
	v_mfma_f32_16x16x32_bf16 v[84:87], v[140:143], v[200:203], v[84:87]
	v_mfma_f32_16x16x32_bf16 v[120:123], v[132:135], v[208:211], v[120:123]
	v_mfma_f32_16x16x32_bf16 v[92:95], v[140:143], v[208:211], v[92:95]
	s_waitcnt lgkmcnt(0)
	v_mfma_f32_16x16x32_bf16 v[124:127], v[132:135], v[236:239], v[124:127]
	v_mfma_f32_16x16x32_bf16 v[96:99], v[140:143], v[236:239], v[96:99]
	s_barrier
	ds_read_b128 v[240:243], v177 offset:16384
	ds_read_b128 v[244:247], v177 offset:17408
	ds_read_b128 v[248:251], v177 offset:18432
	ds_read_b128 v[230:233], v177 offset:19456
	s_and_b64 s[48:49], s[82:83], exec
	s_cselect_b32 s76, s0, s1
	s_cselect_b32 s77, s69, s9
	s_mov_b32 m0, s28
	s_nop 0
	global_load_lds_dwordx4 v152, s[76:77]
	s_add_u32 s48, s76, 0x2000
	s_addc_u32 s49, s77, 0
	s_mov_b32 m0, s29
	s_nop 0
	global_load_lds_dwordx4 v152, s[48:49]
	s_waitcnt vmcnt(10)
	s_barrier
	s_waitcnt lgkmcnt(3)
	v_mfma_f32_16x16x32_bf16 v[48:51], v[240:243], v[144:147], 0
	s_waitcnt lgkmcnt(1)
	v_mfma_f32_16x16x32_bf16 v[16:19], v[248:251], v[144:147], 0
	v_mfma_f32_16x16x32_bf16 v[52:55], v[240:243], v[184:187], 0
	v_mfma_f32_16x16x32_bf16 v[20:23], v[248:251], v[184:187], 0
	v_mfma_f32_16x16x32_bf16 v[56:59], v[240:243], v[204:207], 0
	v_mfma_f32_16x16x32_bf16 v[24:27], v[248:251], v[204:207], 0
	v_mfma_f32_16x16x32_bf16 v[60:63], v[240:243], v[212:215], 0
	v_mfma_f32_16x16x32_bf16 v[28:31], v[248:251], v[212:215], 0
	v_mfma_f32_16x16x32_bf16 v[48:51], v[244:247], v[148:151], v[48:51]
	s_waitcnt lgkmcnt(0)
	v_mfma_f32_16x16x32_bf16 v[16:19], v[230:233], v[148:151], v[16:19]
	v_mfma_f32_16x16x32_bf16 v[52:55], v[244:247], v[200:203], v[52:55]
	v_mfma_f32_16x16x32_bf16 v[20:23], v[230:233], v[200:203], v[20:23]
	v_mfma_f32_16x16x32_bf16 v[56:59], v[244:247], v[208:211], v[56:59]
	v_mfma_f32_16x16x32_bf16 v[24:27], v[230:233], v[208:211], v[24:27]
	v_mfma_f32_16x16x32_bf16 v[60:63], v[244:247], v[236:239], v[60:63]
	v_mfma_f32_16x16x32_bf16 v[28:31], v[230:233], v[236:239], v[28:31]
	s_barrier
	ds_read_b128 v[144:147], v178 offset:16384
	ds_read_b128 v[148:151], v178 offset:17408
	ds_read_b128 v[184:187], v178 offset:18432
	ds_read_b128 v[200:203], v178 offset:19456
	ds_read_b128 v[204:207], v178 offset:20480
	ds_read_b128 v[208:211], v178 offset:21504
	ds_read_b128 v[212:215], v178 offset:22528
	ds_read_b128 v[236:239], v178 offset:23552
	s_mov_b32 m0, s89
	s_nop 0
	global_load_lds_dwordx4 v152, s[80:81]
	s_add_u32 s48, s80, 0x2000
	s_addc_u32 s49, s81, 0
	s_mov_b32 m0, s40
	s_nop 0
	global_load_lds_dwordx4 v152, s[48:49]
	s_waitcnt vmcnt(10)
	s_barrier
	s_waitcnt lgkmcnt(7)
	v_mfma_f32_16x16x32_bf16 v[100:103], v[128:131], v[144:147], 0
	v_mfma_f32_16x16x32_bf16 v[64:67], v[136:139], v[144:147], 0
	s_waitcnt lgkmcnt(5)
	v_mfma_f32_16x16x32_bf16 v[104:107], v[128:131], v[184:187], 0
	v_mfma_f32_16x16x32_bf16 v[68:71], v[136:139], v[184:187], 0
	s_waitcnt lgkmcnt(3)
	v_mfma_f32_16x16x32_bf16 v[108:111], v[128:131], v[204:207], 0
	v_mfma_f32_16x16x32_bf16 v[72:75], v[136:139], v[204:207], 0
	s_waitcnt lgkmcnt(1)
	v_mfma_f32_16x16x32_bf16 v[112:115], v[128:131], v[212:215], 0
	v_mfma_f32_16x16x32_bf16 v[76:79], v[136:139], v[212:215], 0
	v_mfma_f32_16x16x32_bf16 v[100:103], v[132:135], v[148:151], v[100:103]
	v_mfma_f32_16x16x32_bf16 v[64:67], v[140:143], v[148:151], v[64:67]
	v_mfma_f32_16x16x32_bf16 v[104:107], v[132:135], v[200:203], v[104:107]
	v_mfma_f32_16x16x32_bf16 v[68:71], v[140:143], v[200:203], v[68:71]
	v_mfma_f32_16x16x32_bf16 v[108:111], v[132:135], v[208:211], v[108:111]
	v_mfma_f32_16x16x32_bf16 v[72:75], v[140:143], v[208:211], v[72:75]
	s_waitcnt lgkmcnt(0)
	v_mfma_f32_16x16x32_bf16 v[112:115], v[132:135], v[236:239], v[112:115]
	v_mfma_f32_16x16x32_bf16 v[76:79], v[140:143], v[236:239], v[76:79]
	s_barrier
; #define PG8_STAGE(bufoff, gbase, hoff, imm) do { _Pragma("unroll") for (int _i = 0; _i < 2; ++_i) { \
;         asm volatile("s_mov_b32 m0, %0\n\ts_nop 0\n\tglobal_load_lds_dwordx4 %1, %2" \
;             :: "s"(lds0 + (unsigned)((bufoff) + _i * 8192)), "v"(voff0), "s"((const char*)(gbase) + (size_t)(hoff) + (size_t)(_i * 8192)) : "memory"); } } while (0)
; #define PG8_LDA(dst, b, h) do { _Pragma("unroll") for (int m = 0; m < 4; ++m) _Pragma("unroll") for (int k = 0; k < 2; ++k) dst[m][k] = *(const LAS bf16x8*)(lds + PG8_SA(b, h) + aoff + m * 2048 + k * 1024); } while (0)
; #define PG8_LDB(dst, b, h) do { _Pragma("unroll") for (int n = 0; n < 2; ++n) _Pragma("unroll") for (int k = 0; k < 2; ++k) dst[n][k] = *(const LAS bf16x8*)(lds + PG8_SB(b, h) + boff + n * 2048 + k * 1024); } while (0)
; #define PG8_MMA(ai, bj, At, Bt) do { __builtin_amdgcn_s_setprio(1); _Pragma("unroll") for (int m = 0; m < 4; ++m) _Pragma("unroll") for (int n = 0; n < 2; ++n) _Pragma("unroll") for (int k = 0; k < 2; ++k) \
;         acc[ai][bj][m][n] = __builtin_amdgcn_mfma_f32_16x16x32_bf16(Bt[n][k], At[m][k], acc[ai][bj][m][n], 0, 0, 0); __builtin_amdgcn_s_setprio(0); } while (0)
; #define PG8_WAIT_V(n) asm volatile("s_waitcnt vmcnt(" #n ")" ::: "memory")
; #define PG8_WAIT_L(n) asm volatile("s_waitcnt lgkmcnt(" #n ")" ::: "memory")
; template <class Epi>
; __device__ __forceinline__ void gemm_phase(LAS unsigned char* lds, const Gemm g, const StaticOrder& S, const Epi& E) {
;     ...
;             PG8_LDA(At, 0, 1); PG8_STAGE(PG8_SA(0, 0), a2, 0, 0);
;             PG8_BAR; PG8_WAIT_L(0); PG8_MMA(1, 0, At, B0); PG8_BAR; PG8_SCHED;
;             PG8_STAGE(PG8_SB(0, 1), b2, hB, 0);
;             PG8_WAIT_V(6); PG8_BAR; PG8_MMA(1, 1, At, B1); PG8_BAR;
;             PG8_LDB(B0, 1, 0); PG8_SCHED; PG8_LDA(At, 1, 0); PG8_STAGE(PG8_SA(0, 1), a2, hA, 0);
;             PG8_WAIT_L(8); PG8_BAR; PG8_WAIT_L(0); PG8_MMA(0, 0, At, B0); PG8_BAR; PG8_SCHED;
;             PG8_LDB(B1, 1, 1); PG8_STAGE(PG8_SB(1, 0), b2 + KS, 0, 0);
;             PG8_BAR; PG8_WAIT_L(0); PG8_MMA(0, 1, At, B1); PG8_BAR;
;             PG8_LDA(At, 1, 1); PG8_STAGE(PG8_SA(1, 0), a2 + KS, 0, 0);
;             PG8_BAR; PG8_WAIT_L(0); PG8_MMA(1, 0, At, B0); PG8_BAR; PG8_SCHED;
;             PG8_STAGE(PG8_SB(1, 1), b2 + KS, hB, 0);
;             PG8_WAIT_V(6); PG8_BAR; PG8_MMA(1, 1, At, B1); PG8_BAR;
	ds_read_b128 v[128:131], v177 offset:32768
	ds_read_b128 v[132:135], v177 offset:33792
	ds_read_b128 v[136:139], v177 offset:34816
	ds_read_b128 v[140:143], v177 offset:35840
	s_add_u32 s48, s76, 0x80000
	s_addc_u32 s49, s77, 0
	s_mov_b32 m0, s41
	s_nop 0
	global_load_lds_dwordx4 v152, s[48:49]
	s_add_u32 s48, s76, 0x82000
	s_addc_u32 s49, s77, 0
	s_mov_b32 m0, s42
	s_nop 0
	global_load_lds_dwordx4 v152, s[48:49]
	s_add_u32 s48, s80, 0x80000
	s_addc_u32 s49, s81, 0
	s_mov_b32 m0, s43
	s_nop 0
	global_load_lds_dwordx4 v152, s[48:49]
	s_add_u32 s48, s80, 0x82000
	s_addc_u32 s49, s81, 0
	s_mov_b32 m0, s92
	s_nop 0
	global_load_lds_dwordx4 v152, s[48:49]
	s_waitcnt vmcnt(12)
	s_barrier
	v_mfma_f32_16x16x32_bf16 v[32:35], v[240:243], v[144:147], 0
	v_mfma_f32_16x16x32_bf16 v[0:3], v[248:251], v[144:147], 0
	v_mfma_f32_16x16x32_bf16 v[36:39], v[240:243], v[184:187], 0
	v_mfma_f32_16x16x32_bf16 v[4:7], v[248:251], v[184:187], 0
	v_mfma_f32_16x16x32_bf16 v[40:43], v[240:243], v[204:207], 0
	v_mfma_f32_16x16x32_bf16 v[8:11], v[248:251], v[204:207], 0
	v_mfma_f32_16x16x32_bf16 v[44:47], v[240:243], v[212:215], 0
	v_mfma_f32_16x16x32_bf16 v[12:15], v[248:251], v[212:215], 0
	v_mfma_f32_16x16x32_bf16 v[32:35], v[244:247], v[148:151], v[32:35]
	v_mfma_f32_16x16x32_bf16 v[0:3], v[230:233], v[148:151], v[0:3]
	v_mfma_f32_16x16x32_bf16 v[36:39], v[244:247], v[200:203], v[36:39]
	v_mfma_f32_16x16x32_bf16 v[4:7], v[230:233], v[200:203], v[4:7]
	v_mfma_f32_16x16x32_bf16 v[40:43], v[244:247], v[208:211], v[40:43]
	v_mfma_f32_16x16x32_bf16 v[8:11], v[230:233], v[208:211], v[8:11]
	v_mfma_f32_16x16x32_bf16 v[44:47], v[244:247], v[236:239], v[44:47]
	v_mfma_f32_16x16x32_bf16 v[12:15], v[230:233], v[236:239], v[12:15]
	s_barrier
	ds_read_b128 v[144:147], v178 offset:32768
	ds_read_b128 v[148:151], v178 offset:33792
	ds_read_b128 v[184:187], v178 offset:34816
	ds_read_b128 v[200:203], v178 offset:35840
	ds_read_b128 v[204:207], v178 offset:36864
	ds_read_b128 v[208:211], v178 offset:37888
	ds_read_b128 v[212:215], v178 offset:38912
	ds_read_b128 v[230:233], v178 offset:39936
	s_waitcnt lgkmcnt(8)
	s_waitcnt vmcnt(10)
	s_barrier
	s_waitcnt lgkmcnt(7)
	v_mfma_f32_16x16x32_bf16 v[116:119], v[128:131], v[144:147], v[116:119]
	v_mfma_f32_16x16x32_bf16 v[80:83], v[136:139], v[144:147], v[80:83]
	s_waitcnt lgkmcnt(5)
	v_mfma_f32_16x16x32_bf16 v[88:91], v[128:131], v[184:187], v[88:91]
	v_mfma_f32_16x16x32_bf16 v[84:87], v[136:139], v[184:187], v[84:87]
	s_waitcnt lgkmcnt(3)
	v_mfma_f32_16x16x32_bf16 v[120:123], v[128:131], v[204:207], v[120:123]
	v_mfma_f32_16x16x32_bf16 v[92:95], v[136:139], v[204:207], v[92:95]
	s_waitcnt lgkmcnt(1)
	v_mfma_f32_16x16x32_bf16 v[124:127], v[128:131], v[212:215], v[124:127]
	v_mfma_f32_16x16x32_bf16 v[96:99], v[136:139], v[212:215], v[96:99]
	v_mfma_f32_16x16x32_bf16 v[116:119], v[132:135], v[148:151], v[116:119]
	v_mfma_f32_16x16x32_bf16 v[80:83], v[140:143], v[148:151], v[80:83]
	v_mfma_f32_16x16x32_bf16 v[88:91], v[132:135], v[200:203], v[88:91]
	v_mfma_f32_16x16x32_bf16 v[84:87], v[140:143], v[200:203], v[84:87]
	v_mfma_f32_16x16x32_bf16 v[120:123], v[132:135], v[208:211], v[120:123]
	v_mfma_f32_16x16x32_bf16 v[92:95], v[140:143], v[208:211], v[92:95]
	s_waitcnt lgkmcnt(0)
	v_mfma_f32_16x16x32_bf16 v[124:127], v[132:135], v[230:233], v[124:127]
	v_mfma_f32_16x16x32_bf16 v[96:99], v[140:143], v[230:233], v[96:99]
	s_barrier
	ds_read_b128 v[236:239], v177 offset:49152
	ds_read_b128 v[240:243], v177 offset:50176
	ds_read_b128 v[244:247], v177 offset:51200
	ds_read_b128 v[248:251], v177 offset:52224
	s_add_u32 s48, s76, 0x4000
	s_addc_u32 s49, s77, 0
	s_mov_b32 m0, s16
	s_nop 0
	global_load_lds_dwordx4 v152, s[48:49]
	s_add_u32 s48, s76, 0x6000
	s_addc_u32 s49, s77, 0
	s_mov_b32 m0, s17
	s_nop 0
	global_load_lds_dwordx4 v152, s[48:49]
	s_waitcnt vmcnt(10)
	s_barrier
; #define PG8_STAGE(bufoff, gbase, hoff, imm) do { _Pragma("unroll") for (int _i = 0; _i < 2; ++_i) { \
;         asm volatile("s_mov_b32 m0, %0\n\ts_nop 0\n\tglobal_load_lds_dwordx4 %1, %2" \
;             :: "s"(lds0 + (unsigned)((bufoff) + _i * 8192)), "v"(voff0), "s"((const char*)(gbase) + (size_t)(hoff) + (size_t)(_i * 8192)) : "memory"); } } while (0)
; #define PG8_LDA(dst, b, h) do { _Pragma("unroll") for (int m = 0; m < 4; ++m) _Pragma("unroll") for (int k = 0; k < 2; ++k) dst[m][k] = *(const LAS bf16x8*)(lds + PG8_SA(b, h) + aoff + m * 2048 + k * 1024); } while (0)
; #define PG8_LDB(dst, b, h) do { _Pragma("unroll") for (int n = 0; n < 2; ++n) _Pragma("unroll") for (int k = 0; k < 2; ++k) dst[n][k] = *(const LAS bf16x8*)(lds + PG8_SB(b, h) + boff + n * 2048 + k * 1024); } while (0)
; #define PG8_MMA(ai, bj, At, Bt) do { __builtin_amdgcn_s_setprio(1); _Pragma("unroll") for (int m = 0; m < 4; ++m) _Pragma("unroll") for (int n = 0; n < 2; ++n) _Pragma("unroll") for (int k = 0; k < 2; ++k) \
;         acc[ai][bj][m][n] = __builtin_amdgcn_mfma_f32_16x16x32_bf16(Bt[n][k], At[m][k], acc[ai][bj][m][n], 0, 0, 0); __builtin_amdgcn_s_setprio(0); } while (0)
; #define PG8_WAIT_V(n) asm volatile("s_waitcnt vmcnt(" #n ")" ::: "memory")
; #define PG8_WAIT_L(n) asm volatile("s_waitcnt lgkmcnt(" #n ")" ::: "memory")
; #define PG8_BAR __builtin_amdgcn_s_barrier()
; #define PG8_SCHED __builtin_amdgcn_sched_barrier(0)
; template <class Epi>
; __device__ __forceinline__ void gemm_phase(LAS unsigned char* lds, const Gemm g, const StaticOrder& S, const Epi& E) {
;     ...
;             PG8_LDB(B0, 1, 0); PG8_SCHED; PG8_LDA(At, 1, 0); PG8_STAGE(PG8_SA(0, 1), a2, hA, 0);
;             PG8_WAIT_L(8); PG8_BAR; PG8_WAIT_L(0); PG8_MMA(0, 0, At, B0); PG8_BAR; PG8_SCHED;
;             PG8_LDB(B1, 1, 1); PG8_STAGE(PG8_SB(1, 0), b2 + KS, 0, 0);
;             PG8_BAR; PG8_WAIT_L(0); PG8_MMA(0, 1, At, B1); PG8_BAR;
;             PG8_LDA(At, 1, 1); PG8_STAGE(PG8_SA(1, 0), a2 + KS, 0, 0);
;             PG8_BAR; PG8_WAIT_L(0); PG8_MMA(1, 0, At, B0); PG8_BAR; PG8_SCHED;
;             PG8_STAGE(PG8_SB(1, 1), b2 + KS, hB, 0);
;             PG8_WAIT_V(6); PG8_BAR; PG8_MMA(1, 1, At, B1); PG8_BAR;
	s_waitcnt lgkmcnt(3)
	v_mfma_f32_16x16x32_bf16 v[48:51], v[236:239], v[144:147], v[48:51]
	s_waitcnt lgkmcnt(1)
	v_mfma_f32_16x16x32_bf16 v[16:19], v[244:247], v[144:147], v[16:19]
	v_mfma_f32_16x16x32_bf16 v[52:55], v[236:239], v[184:187], v[52:55]
	v_mfma_f32_16x16x32_bf16 v[20:23], v[244:247], v[184:187], v[20:23]
	v_mfma_f32_16x16x32_bf16 v[56:59], v[236:239], v[204:207], v[56:59]
	v_mfma_f32_16x16x32_bf16 v[24:27], v[244:247], v[204:207], v[24:27]
	v_mfma_f32_16x16x32_bf16 v[60:63], v[236:239], v[212:215], v[60:63]
	v_mfma_f32_16x16x32_bf16 v[28:31], v[244:247], v[212:215], v[28:31]
	v_mfma_f32_16x16x32_bf16 v[48:51], v[240:243], v[148:151], v[48:51]
	s_waitcnt lgkmcnt(0)
	v_mfma_f32_16x16x32_bf16 v[16:19], v[248:251], v[148:151], v[16:19]
	v_mfma_f32_16x16x32_bf16 v[52:55], v[240:243], v[200:203], v[52:55]
	v_mfma_f32_16x16x32_bf16 v[20:23], v[248:251], v[200:203], v[20:23]
	v_mfma_f32_16x16x32_bf16 v[56:59], v[240:243], v[208:211], v[56:59]
	v_mfma_f32_16x16x32_bf16 v[24:27], v[248:251], v[208:211], v[24:27]
	v_mfma_f32_16x16x32_bf16 v[60:63], v[240:243], v[230:233], v[60:63]
	v_mfma_f32_16x16x32_bf16 v[28:31], v[248:251], v[230:233], v[28:31]
	s_barrier
	ds_read_b128 v[144:147], v178 offset:49152
	ds_read_b128 v[148:151], v178 offset:50176
	ds_read_b128 v[184:187], v178 offset:51200
	ds_read_b128 v[200:203], v178 offset:52224
	ds_read_b128 v[204:207], v178 offset:53248
	ds_read_b128 v[208:211], v178 offset:54272
	ds_read_b128 v[212:215], v178 offset:55296
	ds_read_b128 v[230:233], v178 offset:56320
	s_add_u32 s48, s80, 0x4000
	s_addc_u32 s49, s81, 0
	s_mov_b32 m0, s24
	s_nop 0
	global_load_lds_dwordx4 v152, s[48:49]
	s_add_u32 s48, s80, 0x6000
	s_addc_u32 s49, s81, 0
	s_mov_b32 m0, s37
	s_nop 0
	global_load_lds_dwordx4 v152, s[48:49]
	s_waitcnt vmcnt(10)
	s_barrier
	s_waitcnt lgkmcnt(7)
	v_mfma_f32_16x16x32_bf16 v[100:103], v[128:131], v[144:147], v[100:103]
	v_mfma_f32_16x16x32_bf16 v[64:67], v[136:139], v[144:147], v[64:67]
	s_waitcnt lgkmcnt(5)
	v_mfma_f32_16x16x32_bf16 v[104:107], v[128:131], v[184:187], v[104:107]
	v_mfma_f32_16x16x32_bf16 v[68:71], v[136:139], v[184:187], v[68:71]
	s_waitcnt lgkmcnt(3)
	v_mfma_f32_16x16x32_bf16 v[108:111], v[128:131], v[204:207], v[108:111]
	v_mfma_f32_16x16x32_bf16 v[72:75], v[136:139], v[204:207], v[72:75]
	s_waitcnt lgkmcnt(1)
	v_mfma_f32_16x16x32_bf16 v[112:115], v[128:131], v[212:215], v[112:115]
	v_mfma_f32_16x16x32_bf16 v[76:79], v[136:139], v[212:215], v[76:79]
	v_mfma_f32_16x16x32_bf16 v[100:103], v[132:135], v[148:151], v[100:103]
	v_mfma_f32_16x16x32_bf16 v[64:67], v[140:143], v[148:151], v[64:67]
	v_mfma_f32_16x16x32_bf16 v[104:107], v[132:135], v[200:203], v[104:107]
	v_mfma_f32_16x16x32_bf16 v[68:71], v[140:143], v[200:203], v[68:71]
	v_mfma_f32_16x16x32_bf16 v[108:111], v[132:135], v[208:211], v[108:111]
	v_mfma_f32_16x16x32_bf16 v[72:75], v[140:143], v[208:211], v[72:75]
	s_waitcnt lgkmcnt(0)
	v_mfma_f32_16x16x32_bf16 v[112:115], v[132:135], v[230:233], v[112:115]
	v_mfma_f32_16x16x32_bf16 v[76:79], v[140:143], v[230:233], v[76:79]
	s_barrier
	ds_read_b128 v[128:131], v177
	ds_read_b128 v[132:135], v177 offset:1024
	ds_read_b128 v[136:139], v177 offset:2048
	ds_read_b128 v[140:143], v177 offset:3072
	s_add_u32 s48, s76, 0x84000
	s_addc_u32 s49, s77, 0
	s_mov_b32 m0, s97
	s_nop 0
	global_load_lds_dwordx4 v152, s[48:49]
	s_add_u32 s48, s76, 0x86000
	s_addc_u32 s49, s77, 0
	s_mov_b32 m0, s38
	s_nop 0
	global_load_lds_dwordx4 v152, s[48:49]
	s_add_u32 s48, s80, 0x84000
	s_addc_u32 s49, s81, 0
	s_mov_b32 m0, s34
	s_nop 0
	global_load_lds_dwordx4 v152, s[48:49]
	s_add_u32 s48, s80, 0x86000
	s_addc_u32 s49, s81, 0
	s_mov_b32 m0, s25
	s_nop 0
	global_load_lds_dwordx4 v152, s[48:49]
	s_waitcnt vmcnt(12)
	s_barrier
	v_mfma_f32_16x16x32_bf16 v[32:35], v[236:239], v[144:147], v[32:35]
	v_mfma_f32_16x16x32_bf16 v[0:3], v[244:247], v[144:147], v[0:3]
	v_mfma_f32_16x16x32_bf16 v[36:39], v[236:239], v[184:187], v[36:39]
	v_mfma_f32_16x16x32_bf16 v[4:7], v[244:247], v[184:187], v[4:7]
	v_mfma_f32_16x16x32_bf16 v[40:43], v[236:239], v[204:207], v[40:43]
	v_mfma_f32_16x16x32_bf16 v[8:11], v[244:247], v[204:207], v[8:11]
	v_mfma_f32_16x16x32_bf16 v[44:47], v[236:239], v[212:215], v[44:47]
	v_mfma_f32_16x16x32_bf16 v[12:15], v[244:247], v[212:215], v[12:15]
	v_mfma_f32_16x16x32_bf16 v[32:35], v[240:243], v[148:151], v[32:35]
	v_mfma_f32_16x16x32_bf16 v[0:3], v[248:251], v[148:151], v[0:3]
	v_mfma_f32_16x16x32_bf16 v[36:39], v[240:243], v[200:203], v[36:39]
	v_mfma_f32_16x16x32_bf16 v[4:7], v[248:251], v[200:203], v[4:7]
	v_mfma_f32_16x16x32_bf16 v[40:43], v[240:243], v[208:211], v[40:43]
	v_mfma_f32_16x16x32_bf16 v[8:11], v[248:251], v[208:211], v[8:11]
	v_mfma_f32_16x16x32_bf16 v[44:47], v[240:243], v[230:233], v[44:47]
	v_mfma_f32_16x16x32_bf16 v[12:15], v[248:251], v[230:233], v[12:15]
	s_add_i32 s71, s71, 2
	s_add_u32 s1, s1, 0x8000
	s_addc_u32 s9, s9, 0
	s_cmp_gt_u32 s71, 29
	s_mov_b64 s[76:77], s[78:79]
	s_barrier
	s_branch .LBB0_739

; #define PG8_WAIT_V(n) asm volatile("s_waitcnt vmcnt(" #n ")" ::: "memory")
; #define PG8_BAR __builtin_amdgcn_s_barrier()
; template <class Epi>
; __device__ __forceinline__ void gemm_phase(LAS unsigned char* lds, const Gemm g, const StaticOrder& S, const Epi& E) {
;     ...
;     PG8_WAIT_V(0);
;     if (wr == 0) PG8_BAR;
;     PG8_BAR;
.LBB0_741:
	v_readfirstlane_b32 s48, v235
	s_nop 1
	s_cmpk_lt_u32 s48, 0x100
	s_cbranch_scc0 .Lup_al_skip
	s_barrier

; #define PG8_WAIT_V(n) asm volatile("s_waitcnt vmcnt(" #n ")" ::: "memory")
; #define PG8_BAR __builtin_amdgcn_s_barrier()
; template <class Epi>
; __device__ __forceinline__ void gemm_phase(LAS unsigned char* lds, const Gemm g, const StaticOrder& S, const Epi& E) {
;     ...
;     PG8_WAIT_V(0);
;     if (wr == 0) PG8_BAR;
;     PG8_BAR;
.LBB0_762:
	s_waitcnt vmcnt(0)
	s_andn2_b64 vcc, exec, s[62:63]
	v_readlane_b32 s38, v255, 44
	s_movk_i32 s30, 0x7ff
	v_readlane_b32 s21, v255, 48
	s_cbranch_vccnz .LBB0_764
.LBB0_764:
	v_readlane_b32 s96, v255, 3
	v_readlane_b32 s97, v255, 4
	s_mov_b32 s88, s86
	s_barrier
